# extra 32 mLSTM scan units on wave 2 (another SIMD than wave 0) of WGs 0..31
# baseline (speedup 1.0000x reference)
.LBB0_316:
	s_or_b64 exec, exec, s[4:5]
	s_mov_b32 s101, 0
	s_add_u32 s1, s68, 0x162e0800
	s_addc_u32 s26, s69, 0
	s_add_u32 s46, s68, 0x1d00800
	v_mov_b32_e32 v183, v254
	s_addc_u32 s47, s69, 0
	v_mbcnt_lo_u32_b32 v0, -1, 0
	s_barrier
	s_add_u32 s27, s68, 0x1f2e0800
	v_and_b32_e32 v182, 63, v183
	v_mbcnt_hi_u32_b32 v181, -1, v0
	v_bfrev_b32_e32 v0, 0.5
	v_readfirstlane_b32 s0, v183
	s_mov_b32 s13, 0
	v_cmp_eq_u32_e64 s[4:5], 0, v182
	s_addc_u32 s52, s69, 0
	v_mov_b32_e32 v157, 0
	s_mov_b32 s53, 0x1e2e0000
	s_mov_b32 s54, 0x1e2e1000
	s_mov_b32 s55, 0x1e2e2000
	s_mov_b32 s70, 0x2280000
	s_mov_b32 s71, 0x2281000
	s_mov_b32 s72, 0x2282000
	s_mov_b32 s73, 0x2283000
	s_mov_b32 s74, 0x2284000
	s_mov_b32 s75, 0x5040100
	s_mov_b64 s[14:15], 0x100
	s_mov_b64 s[16:17], 0x4000
	s_mov_b64 s[18:19], 0x2000
	v_and_b32_e32 v184, 64, v181
	v_lshl_or_b32 v185, v181, 2, v0
	v_mov_b32_e32 v186, 0x3f803f80
	v_mov_b32_e32 v187, 0x80
	s_lshr_b32 s98, s0, 6
	s_cmp_eq_u32 s98, 0
	s_cbranch_scc1 .LBB0_319
	s_cmp_lg_u32 s98, 2
	s_cbranch_scc1 .LBB0_366
	s_cmp_gt_u32 s2, 31
	s_cbranch_scc1 .LBB0_366
	s_branch .LBB0_319
